# k_rope item loop: next item's H fragments requested during the current item's reduction (second register set, copied at the latch)
# speedup vs baseline: 1.0037x; 1.0037x over previous
; DI unsigned pk2(float lo, float hi) { f32x2 v = {lo, hi}; bf16x2_t b = __builtin_convertvector(v, bf16x2_t); return __builtin_bit_cast(unsigned, b); }
; DI float shx(float v, int m, int lane) { return __int_as_float(__builtin_amdgcn_ds_bpermute((lane ^ m) << 2, __float_as_int(v))); }
; DI void krope_phase(const Frame& F, int crank, int ncu) {
;     ...
;         const bf16_t* hp = H + (size_t)(row0 + r32) * 1024 + 8 * h5 + 128 * w; const bf16_t* wp = Wk + (size_t)r32 * 1024 + 8 * h5 + 128 * w;
;         bf16x8 a[8], b[8];
; #pragma unroll
;         for (int q = 0; q < 8; ++q) { a[q] = *(const bf16x8*)(wp + 16 * q); b[q] = *(const bf16x8*)(hp + 16 * q); }
;     ...
;             const int row = row0 + r32;
;             f32x16 oth;
; #pragma unroll
;             for (int i = 0; i < 16; ++i) oth[i] = shx(acc[i], 32, F.lane);
;             u32x2 wv[4];
; #pragma unroll
;             for (int g = 0; g < 4; ++g) { float o[4];
; #pragma unroll
;                 for (int e = 0; e < 4; ++e) { const int i = 4 * g + e; float x1 = h5 ? oth[i] : acc[i], x2 = h5 ? acc[i] : oth[i]; float cs = 1.f, sn = 0.f;
;                     if (row < ML) { cs = rm[(size_t)(row & 2047) * 32 + i]; sn = rm[(size_t)(row & 2047) * 32 + 16 + i]; }
;                     o[e] = h5 ? (x1 * sn + x2 * cs) : (x1 * cs - x2 * sn); }
;                 wv[g].x = pk2(o[0], o[1]); wv[g].y = pk2(o[2], o[3]); }
; #pragma unroll
;             for (int g = 0; g < 4; ++g) *(u32x2*)(KR + (size_t)row * 32 + 8 * g + 4 * h5) = wv[g];
.LBB0_537:
	s_andn2_b64 vcc, exec, s[60:61]
	s_cbranch_vccnz .LBB0_662
	s_cmpk_gt_u32 s96, 0x23f
	s_cbranch_scc1 .LBB0_575
	v_lshrrev_b32_e32 v0, 5, v186
	s_add_u32 s6, s94, 0x200000
	v_lshlrev_b32_e32 v96, 3, v0
	v_lshlrev_b32_e32 v0, 4, v0
	v_mov_b32_e32 v1, v97
	v_readlane_b32 s4, v255, 31
	s_addc_u32 s7, s95, 0
	v_lshl_add_u64 v[2:3], s[94:95], 0, v[0:1]
	s_lshl_b32 s16, s4, 8
	v_and_b32_e32 v4, 31, v225
	v_lshl_add_u64 v[2:3], v[2:3], 0, s[16:17]
	s_mov_b64 s[2:3], 0x3e00000
	v_lshl_add_u64 v[16:17], v[2:3], 0, s[2:3]
	v_lshlrev_b32_e32 v2, 11, v4
	v_mov_b32_e32 v3, v97
	v_lshl_add_u64 v[2:3], s[94:95], 0, v[2:3]
	v_lshl_add_u64 v[0:1], v[2:3], 0, v[0:1]
	v_lshl_add_u64 v[0:1], v[0:1], 0, s[16:17]
	s_mov_b64 s[2:3], 0x1d80000
	v_lshl_add_u64 v[18:19], v[0:1], 0, s[2:3]
	s_lshl_b32 s2, s4, 12
	v_lshl_add_u64 v[0:1], s[94:95], 0, v[96:97]
	s_mov_b64 s[4:5], 0x8f00000
	s_add_i32 s10, s2, 0
	v_readlane_b32 s2, v255, 32
	v_lshl_add_u64 v[20:21], v[0:1], 0, s[4:5]
	v_lshlrev_b32_e32 v0, 2, v186
	s_cmp_lt_u32 s2, 64
	v_add_u32_e32 v22, s10, v0
	v_add_u32_e32 v23, 0, v0
	v_xor_b32_e32 v24, 0x80, v0
	v_lshlrev_b32_e32 v0, 5, v4
	s_cselect_b64 s[8:9], -1, 0
	v_cmp_gt_u32_e64 s[2:3], 32, v186
	v_lshl_or_b32 v96, s96, 5, v4
	s_lshl_b32 s12, s93, 5
	v_lshl_or_b32 v25, s96, 10, v0
	s_lshl_b32 s13, s93, 10
	s_mov_b32 s14, s96
	global_load_dwordx4 v[100:103], v[18:19], off
	global_load_dwordx4 v[104:107], v[18:19], off offset:32
	global_load_dwordx4 v[108:111], v[18:19], off offset:64
	global_load_dwordx4 v[112:115], v[18:19], off offset:96
	global_load_dwordx4 v[116:119], v[18:19], off offset:128
	global_load_dwordx4 v[120:123], v[18:19], off offset:160
	global_load_dwordx4 v[124:127], v[18:19], off offset:192
	global_load_dwordx4 v[128:131], v[18:19], off offset:224
	v_lshlrev_b64 v[4:5], 11, v[96:97]
	v_lshl_add_u64 v[38:39], v[16:17], 0, v[4:5]
	global_load_dwordx4 v[132:135], v[38:39], off
	global_load_dwordx4 v[136:139], v[38:39], off offset:32
	global_load_dwordx4 v[140:143], v[38:39], off offset:64
	global_load_dwordx4 v[144:147], v[38:39], off offset:96
	global_load_dwordx4 v[148:151], v[38:39], off offset:128
	global_load_dwordx4 v[152:155], v[38:39], off offset:160
	global_load_dwordx4 v[156:159], v[38:39], off offset:192
	global_load_dwordx4 v[160:163], v[38:39], off offset:224
	s_branch .LBB0_542
.LBB0_540:
	s_waitcnt lgkmcnt(1)
	v_cndmask_b32_e64 v0, v54, v46, s[2:3]
	v_cndmask_b32_e64 v1, v46, v54, s[2:3]
	s_waitcnt vmcnt(0)
	v_mul_f32_e32 v46, v0, v74
	v_fmac_f32_e32 v46, v1, v75
	v_mul_f32_e32 v1, v1, v74
	v_fma_f32 v0, v0, v75, -v1
	v_cndmask_b32_e64 v46, v46, v0, s[2:3]
	v_cndmask_b32_e64 v0, v51, v40, s[2:3]
	v_cndmask_b32_e64 v1, v40, v51, s[2:3]
	v_mul_f32_e32 v40, v0, v70
	v_fmac_f32_e32 v40, v1, v72
	v_mul_f32_e32 v1, v1, v70
	v_fma_f32 v0, v0, v72, -v1
	v_cndmask_b32_e64 v40, v40, v0, s[2:3]
	v_cndmask_b32_e64 v0, v48, v41, s[2:3]
	v_cndmask_b32_e64 v1, v41, v48, s[2:3]
	v_mul_f32_e32 v41, v0, v73
	v_fmac_f32_e32 v41, v1, v71
	v_mul_f32_e32 v1, v1, v73
	v_fma_f32 v0, v0, v71, -v1
	v_cndmask_b32_e64 v41, v41, v0, s[2:3]
	v_cndmask_b32_e64 v0, v45, v33, s[2:3]
	v_cndmask_b32_e64 v1, v33, v45, s[2:3]
	v_mul_f32_e32 v33, v0, v67
	v_fmac_f32_e32 v33, v1, v69
	v_mul_f32_e32 v1, v1, v67
	v_fma_f32 v0, v0, v69, -v1
	v_cndmask_b32_e64 v1, v33, v0, s[2:3]
	v_cndmask_b32_e64 v0, v44, v34, s[2:3]
	v_cndmask_b32_e64 v33, v34, v44, s[2:3]
	v_cndmask_b32_e64 v34, v43, v13, s[2:3]
	v_cndmask_b32_e64 v13, v13, v43, s[2:3]
	v_mul_f32_e32 v43, v34, v60
	v_fmac_f32_e32 v43, v13, v63
	v_mul_f32_e32 v13, v13, v60
	v_fma_f32 v13, v34, v63, -v13
	v_cndmask_b32_e64 v34, v42, v14, s[2:3]
	v_cndmask_b32_e64 v14, v14, v42, s[2:3]
	v_mul_f32_e32 v42, v34, v64
	v_fmac_f32_e32 v42, v14, v61
	v_mul_f32_e32 v14, v14, v64
	v_fma_f32 v14, v34, v61, -v14
	v_mul_f32_e32 v34, v0, v68
	v_fmac_f32_e32 v34, v33, v66
	v_mul_f32_e32 v33, v33, v68
	v_cndmask_b32_e64 v13, v43, v13, s[2:3]
	v_cndmask_b32_e64 v14, v42, v14, s[2:3]
	v_fma_f32 v0, v0, v66, -v33
	v_cndmask_b32_e64 v33, v34, v0, s[2:3]
	v_cvt_pk_bf16_f32 v0, v13, v14
	v_cndmask_b32_e64 v13, v37, v8, s[2:3]
	v_cndmask_b32_e64 v8, v8, v37, s[2:3]
	v_mul_f32_e32 v14, v13, v57
	v_fmac_f32_e32 v14, v8, v59
	v_mul_f32_e32 v8, v8, v57
	v_fma_f32 v8, v13, v59, -v8
	v_cndmask_b32_e64 v8, v14, v8, s[2:3]
	v_cndmask_b32_e64 v14, v35, v6, s[2:3]
	v_cvt_pk_bf16_f32 v1, v1, v33
	v_cndmask_b32_e64 v6, v6, v35, s[2:3]
	v_mul_f32_e32 v33, v14, v49
	v_fmac_f32_e32 v33, v6, v53
	v_mul_f32_e32 v6, v6, v49
	v_fma_f32 v6, v14, v53, -v6
	v_cndmask_b32_e64 v14, v29, v7, s[2:3]
	v_cndmask_b32_e64 v7, v7, v29, s[2:3]
	v_mul_f32_e32 v29, v14, v55
	v_cndmask_b32_e64 v13, v36, v9, s[2:3]
	v_fmac_f32_e32 v29, v7, v50
	v_mul_f32_e32 v7, v7, v55
	v_cndmask_b32_e64 v9, v9, v36, s[2:3]
	v_fma_f32 v7, v14, v50, -v7
	v_mul_f32_e32 v14, v13, v58
	v_fmac_f32_e32 v14, v9, v56
	v_mul_f32_e32 v9, v9, v58
	v_fma_f32 v9, v13, v56, -v9
	v_cndmask_b32_e64 v6, v33, v6, s[2:3]
	v_cndmask_b32_e64 v7, v29, v7, s[2:3]
	v_cndmask_b32_e64 v9, v14, v9, s[2:3]
	v_cvt_pk_bf16_f32 v6, v6, v7
	v_cvt_pk_bf16_f32 v7, v8, v9
	v_cndmask_b32_e64 v8, v15, v4, s[2:3]
	v_cndmask_b32_e64 v4, v4, v15, s[2:3]
	v_mul_f32_e32 v9, v8, v30
	v_fmac_f32_e32 v9, v4, v39
	v_mul_f32_e32 v4, v4, v30
	v_fma_f32 v4, v8, v39, -v4
	v_cndmask_b32_e64 v4, v9, v4, s[2:3]
	v_cndmask_b32_e64 v9, v11, v2, s[2:3]
	v_cndmask_b32_e64 v2, v2, v11, s[2:3]
	v_mul_f32_e32 v11, v9, v28
	v_fmac_f32_e32 v11, v2, v27
	v_mul_f32_e32 v2, v2, v28
	v_fma_f32 v2, v9, v27, -v2
	v_cndmask_b32_e64 v9, v10, v3, s[2:3]
	v_cndmask_b32_e64 v3, v3, v10, s[2:3]
	v_mul_f32_e32 v10, v9, v31
	v_cndmask_b32_e64 v8, v12, v5, s[2:3]
	v_fmac_f32_e32 v10, v3, v26
	v_mul_f32_e32 v3, v3, v31
	v_cndmask_b32_e64 v5, v5, v12, s[2:3]
	v_fma_f32 v3, v9, v26, -v3
	v_mul_f32_e32 v9, v8, v38
	v_fmac_f32_e32 v9, v5, v32
	v_mul_f32_e32 v5, v5, v38
	v_fma_f32 v5, v8, v32, -v5
	s_waitcnt lgkmcnt(0)
	v_cndmask_b32_e64 v54, v52, v47, s[2:3]
	v_cndmask_b32_e64 v47, v47, v52, s[2:3]
	v_cndmask_b32_e64 v2, v11, v2, s[2:3]
	v_cndmask_b32_e64 v3, v10, v3, s[2:3]
	v_cndmask_b32_e64 v5, v9, v5, s[2:3]
	v_cvt_pk_bf16_f32 v2, v2, v3
	v_cvt_pk_bf16_f32 v3, v4, v5
	v_mul_f32_e32 v4, v54, v65
	v_mul_f32_e32 v5, v47, v65
	v_fmac_f32_e32 v4, v47, v62
	v_fma_f32 v5, v54, v62, -v5
	v_lshlrev_b64 v[8:9], 6, v[96:97]
	v_cndmask_b32_e64 v5, v4, v5, s[2:3]
	v_lshl_add_u64 v[8:9], v[20:21], 0, v[8:9]
	v_cvt_pk_bf16_f32 v4, v40, v41
	v_cvt_pk_bf16_f32 v5, v46, v5
	global_store_dwordx2 v[8:9], v[2:3], off
	global_store_dwordx2 v[8:9], v[6:7], off offset:16
	global_store_dwordx2 v[8:9], v[0:1], off offset:32
	global_store_dwordx2 v[8:9], v[4:5], off offset:48
	s_waitcnt vmcnt(4)
	s_branch .Lkr_copy

; DI void krope_phase(const Frame& F, int crank, int ncu) {
;     ...
;     for (int it = crank; it < MT / 32; it += ncu) {
;         const int row0 = it * 32;
;         f32x16 acc;
; #pragma unroll
;         for (int i = 0; i < 16; ++i) acc[i] = 0.f;
;         const bf16_t* hp = H + (size_t)(row0 + r32) * 1024 + 8 * h5 + 128 * w; const bf16_t* wp = Wk + (size_t)r32 * 1024 + 8 * h5 + 128 * w;
;         bf16x8 a[8], b[8];
; #pragma unroll
;         for (int q = 0; q < 8; ++q) { a[q] = *(const bf16x8*)(wp + 16 * q); b[q] = *(const bf16x8*)(hp + 16 * q); }
.Lkr_copy:
	v_mov_b64_e32 v[132:133], v[188:189]
	v_mov_b64_e32 v[134:135], v[190:191]
	v_mov_b64_e32 v[136:137], v[192:193]
	v_mov_b64_e32 v[138:139], v[194:195]
	v_mov_b64_e32 v[140:141], v[196:197]
	v_mov_b64_e32 v[142:143], v[198:199]
	v_mov_b64_e32 v[144:145], v[200:201]
	v_mov_b64_e32 v[146:147], v[202:203]
	v_mov_b64_e32 v[148:149], v[204:205]
	v_mov_b64_e32 v[150:151], v[206:207]
	v_mov_b64_e32 v[152:153], v[208:209]
	v_mov_b64_e32 v[154:155], v[210:211]
	v_mov_b64_e32 v[156:157], v[228:229]
	v_mov_b64_e32 v[158:159], v[230:231]
	v_mov_b64_e32 v[160:161], v[232:233]
	v_mov_b64_e32 v[162:163], v[234:235]

; DI void krope_phase(const Frame& F, int crank, int ncu) {
;     ...
;     for (int it = crank; it < MT / 32; it += ncu) {
;     ...
;         const bf16_t* hp = H + (size_t)(row0 + r32) * 1024 + 8 * h5 + 128 * w; const bf16_t* wp = Wk + (size_t)r32 * 1024 + 8 * h5 + 128 * w;
;         bf16x8 a[8], b[8];
; #pragma unroll
;         for (int q = 0; q < 8; ++q) { a[q] = *(const bf16x8*)(wp + 16 * q); b[q] = *(const bf16x8*)(hp + 16 * q); }
.LBB0_542:
	s_add_i32 s15, s14, s93
	s_cmpk_lt_u32 s15, 0x240
	s_cbranch_scc0 .Lkr_np
	v_add_u32_e32 v84, s12, v96
	v_mov_b32_e32 v85, v97
	v_lshlrev_b64 v[86:87], 11, v[84:85]
	v_lshl_add_u64 v[88:89], v[16:17], 0, v[86:87]
	global_load_dwordx4 v[188:191], v[88:89], off
	global_load_dwordx4 v[192:195], v[88:89], off offset:32
	global_load_dwordx4 v[196:199], v[88:89], off offset:64
	global_load_dwordx4 v[200:203], v[88:89], off offset:96
	global_load_dwordx4 v[204:207], v[88:89], off offset:128
	global_load_dwordx4 v[208:211], v[88:89], off offset:160
	global_load_dwordx4 v[228:231], v[88:89], off offset:192
	global_load_dwordx4 v[232:235], v[88:89], off offset:224
	s_waitcnt vmcnt(8)
	s_branch .Lkr_go

; #define MFMA32(a, b, c) __builtin_amdgcn_mfma_f32_32x32x16_bf16((a), (b), (c), 0, 0, 0)
; DI void krope_phase(const Frame& F, int crank, int ncu) {
;     ...
; #pragma unroll
;         for (int q = 0; q < 8; ++q) acc = MFMA32(a[q], b[q], acc);
;         __syncthreads();
; #pragma unroll
;         for (int i = 0; i < 16; ++i) part[(w * 16 + i) * 64 + F.lane] = acc[i];
;         __syncthreads();
;         if (w == 0) {
; #pragma unroll
;             for (int i = 0; i < 16; ++i) { float sacc = 0.f;
; #pragma unroll
;                 for (int q = 0; q < 8; ++q) sacc += part[(q * 16 + i) * 64 + F.lane];
;                 acc[i] = sacc; }
.Lkr_go:
	s_andn2_b64 vcc, exec, s[8:9]
	v_mfma_f32_32x32x16_bf16 v[0:15], v[100:103], v[132:135], 0
	v_mfma_f32_32x32x16_bf16 v[0:15], v[104:107], v[136:139], v[0:15]
	v_mfma_f32_32x32x16_bf16 v[0:15], v[108:111], v[140:143], v[0:15]
	v_mfma_f32_32x32x16_bf16 v[0:15], v[112:115], v[144:147], v[0:15]
	v_mfma_f32_32x32x16_bf16 v[0:15], v[116:119], v[148:151], v[0:15]
	v_mfma_f32_32x32x16_bf16 v[0:15], v[120:123], v[152:155], v[0:15]
	v_mfma_f32_32x32x16_bf16 v[0:15], v[124:127], v[156:159], v[0:15]
	v_mfma_f32_32x32x16_bf16 v[0:15], v[128:131], v[160:163], v[0:15]
	s_waitcnt lgkmcnt(0)
	s_barrier
	s_nop 11
	ds_write2st64_b32 v22, v0, v1 offset1:1
	ds_write2st64_b32 v22, v2, v3 offset0:2 offset1:3
	ds_write2st64_b32 v22, v4, v5 offset0:4 offset1:5
	ds_write2st64_b32 v22, v6, v7 offset0:6 offset1:7
	ds_write2st64_b32 v22, v8, v9 offset0:8 offset1:9
	ds_write2st64_b32 v22, v10, v11 offset0:10 offset1:11
	ds_write2st64_b32 v22, v12, v13 offset0:12 offset1:13
	ds_write2st64_b32 v22, v14, v15 offset0:14 offset1:15
	s_waitcnt lgkmcnt(0)
	s_barrier
	s_cbranch_vccnz .Lkr_lw
	ds_read2st64_b32 v[0:1], v23 offset1:1
	ds_read2st64_b32 v[2:3], v23 offset0:16 offset1:17
	ds_read2st64_b32 v[4:5], v23 offset0:2 offset1:3
	ds_read2st64_b32 v[6:7], v23 offset0:4 offset1:5
	ds_read2st64_b32 v[8:9], v23 offset0:6 offset1:7
	s_waitcnt lgkmcnt(4)
	v_add_f32_e32 v0, 0, v0
	ds_read2st64_b32 v[10:11], v23 offset0:18 offset1:19
	ds_read2st64_b32 v[12:13], v23 offset0:20 offset1:21
	ds_read2st64_b32 v[14:15], v23 offset0:22 offset1:23
	s_waitcnt lgkmcnt(6)
	v_add_f32_e32 v0, v0, v2
	ds_read2st64_b32 v[26:27], v23 offset0:32 offset1:33
	ds_read2st64_b32 v[28:29], v23 offset0:48 offset1:49
	ds_read2st64_b32 v[30:31], v23 offset0:34 offset1:35
	ds_read2st64_b32 v[32:33], v23 offset0:36 offset1:37
	ds_read2st64_b32 v[34:35], v23 offset0:38 offset1:39
	s_waitcnt lgkmcnt(4)
	v_add_f32_e32 v0, v0, v26
	ds_read2st64_b32 v[36:37], v23 offset0:50 offset1:51
	ds_read2st64_b32 v[38:39], v23 offset0:52 offset1:53
	ds_read2st64_b32 v[40:41], v23 offset0:54 offset1:55
	s_waitcnt lgkmcnt(6)
	v_add_f32_e32 v0, v0, v28
	ds_read2st64_b32 v[42:43], v23 offset0:64 offset1:65
	ds_read2st64_b32 v[44:45], v23 offset0:80 offset1:81
	ds_read2st64_b32 v[46:47], v23 offset0:66 offset1:67
	ds_read2st64_b32 v[48:49], v23 offset0:68 offset1:69
	ds_read2st64_b32 v[50:51], v23 offset0:70 offset1:71
	s_waitcnt lgkmcnt(4)
	v_add_f32_e32 v0, v0, v42
	ds_read2st64_b32 v[52:53], v23 offset0:82 offset1:83
	ds_read2st64_b32 v[54:55], v23 offset0:84 offset1:85
	ds_read2st64_b32 v[56:57], v23 offset0:86 offset1:87
	s_waitcnt lgkmcnt(6)
	v_add_f32_e32 v0, v0, v44
	ds_read2st64_b32 v[58:59], v23 offset0:96 offset1:97
	ds_read2st64_b32 v[60:61], v23 offset0:112 offset1:113
	ds_read2st64_b32 v[62:63], v23 offset0:98 offset1:99
	ds_read2st64_b32 v[64:65], v23 offset0:100 offset1:101
	ds_read2st64_b32 v[66:67], v23 offset0:102 offset1:103
	s_waitcnt lgkmcnt(4)
	v_add_f32_e32 v0, v0, v58
	s_waitcnt lgkmcnt(3)
	v_add_f32_e32 v2, v0, v60
	v_add_f32_e32 v0, 0, v1
	v_add_f32_e32 v0, v0, v3
	v_add_f32_e32 v0, v0, v27
	v_add_f32_e32 v0, v0, v29
	v_add_f32_e32 v0, v0, v43
	v_add_f32_e32 v0, v0, v45
	v_add_f32_e32 v0, v0, v59
	v_add_f32_e32 v3, v0, v61
	v_add_f32_e32 v0, 0, v4
	v_add_f32_e32 v0, v0, v10
	v_add_f32_e32 v0, v0, v30
	v_add_f32_e32 v0, v0, v36
	ds_read2st64_b32 v[68:69], v23 offset0:114 offset1:115
	ds_read2st64_b32 v[70:71], v23 offset0:116 offset1:117
	ds_read2st64_b32 v[72:73], v23 offset0:118 offset1:119
	v_add_f32_e32 v0, v0, v46
	v_add_f32_e32 v0, v0, v52
	s_waitcnt lgkmcnt(5)
	v_add_f32_e32 v0, v0, v62
	s_waitcnt lgkmcnt(2)
	v_add_f32_e32 v4, v0, v68
	v_add_f32_e32 v0, 0, v5
	v_add_f32_e32 v0, v0, v11
	v_add_f32_e32 v0, v0, v31
	v_add_f32_e32 v0, v0, v37
	v_add_f32_e32 v0, v0, v47
	v_add_f32_e32 v0, v0, v53
	v_add_f32_e32 v0, v0, v63
	v_add_f32_e32 v5, v0, v69
	v_add_f32_e32 v0, 0, v6
	v_add_f32_e32 v0, v0, v12
	v_add_f32_e32 v0, v0, v32
	v_add_f32_e32 v0, v0, v38
	v_add_f32_e32 v0, v0, v48
	v_add_f32_e32 v0, v0, v54
	v_add_f32_e32 v0, v0, v64
	s_waitcnt lgkmcnt(1)
	v_add_f32_e32 v6, v0, v70
	v_add_f32_e32 v0, 0, v7
	v_add_f32_e32 v0, v0, v13
	v_add_f32_e32 v0, v0, v33
	v_add_f32_e32 v0, v0, v39
	v_add_f32_e32 v0, v0, v49
	v_add_f32_e32 v0, v0, v55
	v_add_f32_e32 v0, v0, v65
	v_add_f32_e32 v7, v0, v71
	v_add_f32_e32 v0, 0, v8
	v_add_f32_e32 v0, v0, v14
	v_add_f32_e32 v0, v0, v34
	v_add_f32_e32 v0, v0, v40
	v_add_f32_e32 v0, v0, v50
	v_add_f32_e32 v0, v0, v56
	v_add_f32_e32 v0, v0, v66
	s_waitcnt lgkmcnt(0)
; DI float shx(float v, int m, int lane) { return __int_as_float(__builtin_amdgcn_ds_bpermute((lane ^ m) << 2, __float_as_int(v))); }
; DI void krope_phase(const Frame& F, int crank, int ncu) {
;     ...
;         if (w == 0) {
; #pragma unroll
;             for (int i = 0; i < 16; ++i) { float sacc = 0.f;
; #pragma unroll
;                 for (int q = 0; q < 8; ++q) sacc += part[(q * 16 + i) * 64 + F.lane];
;                 acc[i] = sacc; }
;             const int row = row0 + r32;
;             f32x16 oth;
; #pragma unroll
;             for (int i = 0; i < 16; ++i) oth[i] = shx(acc[i], 32, F.lane);
;             u32x2 wv[4];
; #pragma unroll
;             for (int g = 0; g < 4; ++g) { float o[4];
; #pragma unroll
;                 for (int e = 0; e < 4; ++e) { const int i = 4 * g + e; float x1 = h5 ? oth[i] : acc[i], x2 = h5 ? acc[i] : oth[i]; float cs = 1.f, sn = 0.f;
;                     if (row < ML) { cs = rm[(size_t)(row & 2047) * 32 + i]; sn = rm[(size_t)(row & 2047) * 32 + 16 + i]; }
	v_add_f32_e32 v8, v0, v72
	v_add_f32_e32 v0, 0, v9
	v_add_f32_e32 v0, v0, v15
	v_add_f32_e32 v0, v0, v35
	v_add_f32_e32 v0, v0, v41
	v_add_f32_e32 v0, v0, v51
	v_add_f32_e32 v0, v0, v57
	v_add_f32_e32 v0, v0, v67
	v_add_f32_e32 v9, v0, v73
	ds_read2st64_b32 v[0:1], v23 offset0:8 offset1:9
	ds_read2st64_b32 v[10:11], v23 offset0:24 offset1:25
	ds_read2st64_b32 v[26:27], v23 offset0:10 offset1:11
	ds_read2st64_b32 v[28:29], v23 offset0:12 offset1:13
	ds_read2st64_b32 v[30:31], v23 offset0:14 offset1:15
	s_waitcnt lgkmcnt(4)
	v_add_f32_e32 v0, 0, v0
	ds_read2st64_b32 v[34:35], v23 offset0:26 offset1:27
	ds_read2st64_b32 v[36:37], v23 offset0:28 offset1:29
	ds_read2st64_b32 v[38:39], v23 offset0:30 offset1:31
	s_waitcnt lgkmcnt(6)
	v_add_f32_e32 v0, v0, v10
	ds_read2st64_b32 v[14:15], v23 offset0:40 offset1:41
	ds_read2st64_b32 v[32:33], v23 offset0:56 offset1:57
	ds_read2st64_b32 v[40:41], v23 offset0:42 offset1:43
	ds_read2st64_b32 v[42:43], v23 offset0:44 offset1:45
	ds_read2st64_b32 v[44:45], v23 offset0:46 offset1:47
	s_waitcnt lgkmcnt(4)
	v_add_f32_e32 v0, v0, v14
	ds_read2st64_b32 v[46:47], v23 offset0:58 offset1:59
	ds_read2st64_b32 v[48:49], v23 offset0:60 offset1:61
	ds_read2st64_b32 v[50:51], v23 offset0:62 offset1:63
	s_waitcnt lgkmcnt(6)
	v_add_f32_e32 v0, v0, v32
	ds_read2st64_b32 v[52:53], v23 offset0:72 offset1:73
	ds_read2st64_b32 v[54:55], v23 offset0:88 offset1:89
	ds_read2st64_b32 v[56:57], v23 offset0:74 offset1:75
	ds_read2st64_b32 v[58:59], v23 offset0:76 offset1:77
	ds_read2st64_b32 v[60:61], v23 offset0:78 offset1:79
	s_waitcnt lgkmcnt(4)
	v_add_f32_e32 v0, v0, v52
	ds_read2st64_b32 v[62:63], v23 offset0:90 offset1:91
	ds_read2st64_b32 v[64:65], v23 offset0:92 offset1:93
	ds_read2st64_b32 v[66:67], v23 offset0:94 offset1:95
	s_waitcnt lgkmcnt(6)
	v_add_f32_e32 v0, v0, v54
	ds_read2st64_b32 v[68:69], v23 offset0:104 offset1:105
	ds_read2st64_b32 v[70:71], v23 offset0:120 offset1:121
	ds_read2st64_b32 v[72:73], v23 offset0:106 offset1:107
	ds_read2st64_b32 v[74:75], v23 offset0:108 offset1:109
	ds_read2st64_b32 v[76:77], v23 offset0:110 offset1:111
	s_waitcnt lgkmcnt(4)
	v_add_f32_e32 v0, v0, v68
	s_waitcnt lgkmcnt(3)
	v_add_f32_e32 v13, v0, v70
	v_add_f32_e32 v0, 0, v1
	v_add_f32_e32 v0, v0, v11
	v_add_f32_e32 v0, v0, v15
	v_add_f32_e32 v0, v0, v33
	v_add_f32_e32 v0, v0, v53
	v_add_f32_e32 v0, v0, v55
	v_add_f32_e32 v0, v0, v69
	v_add_f32_e32 v14, v0, v71
	v_add_f32_e32 v0, 0, v26
	v_add_f32_e32 v0, v0, v34
	v_add_f32_e32 v0, v0, v40
	v_add_f32_e32 v0, v0, v46
	ds_read2st64_b32 v[78:79], v23 offset0:122 offset1:123
	ds_read2st64_b32 v[80:81], v23 offset0:124 offset1:125
	ds_read2st64_b32 v[82:83], v23 offset0:126 offset1:127
	v_add_f32_e32 v0, v0, v56
	v_add_f32_e32 v0, v0, v62
	s_waitcnt lgkmcnt(5)
	v_add_f32_e32 v0, v0, v72
	s_waitcnt lgkmcnt(2)
	v_add_f32_e32 v33, v0, v78
	v_add_f32_e32 v0, 0, v27
	v_add_f32_e32 v0, v0, v35
	v_add_f32_e32 v0, v0, v41
	v_add_f32_e32 v0, v0, v47
	v_add_f32_e32 v0, v0, v57
	v_add_f32_e32 v0, v0, v63
	v_add_f32_e32 v0, v0, v73
	v_add_f32_e32 v34, v0, v79
	v_add_f32_e32 v0, 0, v28
	v_add_f32_e32 v0, v0, v36
	v_add_f32_e32 v0, v0, v42
	v_add_f32_e32 v0, v0, v48
	v_add_f32_e32 v0, v0, v58
	v_add_f32_e32 v0, v0, v64
	v_add_f32_e32 v0, v0, v74
	s_waitcnt lgkmcnt(1)
	v_add_f32_e32 v40, v0, v80
	v_add_f32_e32 v0, 0, v29
	v_add_f32_e32 v0, v0, v37
	v_add_f32_e32 v0, v0, v43
	v_add_f32_e32 v0, v0, v49
	v_add_f32_e32 v0, v0, v59
	v_add_f32_e32 v0, v0, v65
	v_add_f32_e32 v0, v0, v75
	v_add_f32_e32 v41, v0, v81
	v_add_f32_e32 v0, 0, v30
	v_add_f32_e32 v0, v0, v38
	v_add_f32_e32 v0, v0, v44
	v_add_f32_e32 v0, v0, v50
	v_add_f32_e32 v0, v0, v60
	v_add_f32_e32 v0, v0, v66
	v_add_f32_e32 v0, v0, v76
	s_waitcnt lgkmcnt(0)
	v_add_f32_e32 v46, v0, v82
	v_add_f32_e32 v0, 0, v31
	v_add_f32_e32 v0, v0, v39
	v_add_f32_e32 v0, v0, v45
	v_add_f32_e32 v0, v0, v51
	v_add_f32_e32 v0, v0, v61
	v_add_f32_e32 v0, v0, v67
	v_add_f32_e32 v0, v0, v77
	v_add_f32_e32 v47, v0, v83
	ds_bpermute_b32 v11, v24, v2
	ds_bpermute_b32 v10, v24, v3
	ds_bpermute_b32 v15, v24, v4
	ds_bpermute_b32 v12, v24, v5
	ds_bpermute_b32 v35, v24, v6
	ds_bpermute_b32 v29, v24, v7
	ds_bpermute_b32 v37, v24, v8
	ds_bpermute_b32 v36, v24, v9
	ds_bpermute_b32 v43, v24, v13
	ds_bpermute_b32 v42, v24, v14
	ds_bpermute_b32 v45, v24, v33
	ds_bpermute_b32 v44, v24, v34
	ds_bpermute_b32 v51, v24, v40
	ds_bpermute_b32 v48, v24, v41
	ds_bpermute_b32 v54, v24, v46
	ds_bpermute_b32 v52, v24, v47
	v_and_b32_e32 v0, 0xffe0, v25
	s_cmpk_lt_u32 s14, 0x200
	v_lshlrev_b32_e32 v0, 2, v0
	v_mov_b32_e32 v1, v97
	s_cselect_b64 s[10:11], -1, 0
	s_cmpk_gt_u32 s14, 0x1ff
	v_lshl_add_u64 v[0:1], s[6:7], 0, v[0:1]
	v_mov_b32_e32 v30, 0
	v_mov_b32_e32 v26, 1.0
	v_mov_b32_e32 v27, 1.0
	v_mov_b32_e32 v28, 0
	s_cbranch_scc1 .LBB0_545
	global_load_dword v27, v[0:1], off
	global_load_dword v28, v[0:1], off offset:64
